# plus accumulator clearing with v_mov_b64
# speedup vs baseline: 1.0003x; 1.0003x over previous
; template <class Epi, class Sched, bool ALIGN_EPI = false, bool SP2 = false, bool DRAIN = true, bool XR = false>
; __device__ __forceinline__ void gemm_phase(PG8_LAS unsigned char* lds, const Gemm g, const Sched& S, const Epi& E) {
;     ...
; #pragma unroll
;     for (int a = 0; a < 2; ++a)
; #pragma unroll
;         for (int b = 0; b < 2; ++b)
; #pragma unroll
;             for (int m = 0; m < 4; ++m)
; #pragma unroll
;                 for (int n = 0; n < 2; ++n) acc[a][b][m][n] = (f32x4){0.f, 0.f, 0.f, 0.f};
;     ...
;         for (int a = 0; a < 2; ++a)
; #pragma unroll
;             for (int b = 0; b < 2; ++b)
; #pragma unroll
;                 for (int m = 0; m < 4; ++m)
; #pragma unroll
;                     for (int n = 0; n < 2; ++n) acc[a][b][m][n] = (f32x4){0.f, 0.f, 0.f, 0.f};
.LBB0_1018:
	v_mov_b32_e32 v147, 0
	s_andn2_b64 vcc, exec, s[28:29]
	v_mov_b32_e32 v146, 0
	v_mov_b64_e32 v[144:145], 0
	v_mov_b64_e32 v[142:143], 0
	v_mov_b64_e32 v[140:141], 0
	v_mov_b64_e32 v[130:131], 0
	v_mov_b64_e32 v[128:129], 0
	v_mov_b64_e32 v[126:127], 0
	v_mov_b64_e32 v[124:125], 0
	v_mov_b64_e32 v[114:115], 0
	v_mov_b64_e32 v[112:113], 0
	v_mov_b64_e32 v[110:111], 0
	v_mov_b64_e32 v[108:109], 0
	v_mov_b64_e32 v[82:83], 0
	v_mov_b64_e32 v[80:81], 0
	v_mov_b64_e32 v[78:79], 0
	v_mov_b64_e32 v[76:77], 0
	v_mov_b64_e32 v[138:139], 0
	v_mov_b64_e32 v[136:137], 0
	v_mov_b64_e32 v[134:135], 0
	v_mov_b64_e32 v[132:133], 0
	v_mov_b64_e32 v[122:123], 0
	v_mov_b64_e32 v[120:121], 0
	v_mov_b64_e32 v[118:119], 0
	v_mov_b64_e32 v[116:117], 0
	v_mov_b64_e32 v[102:103], 0
	v_mov_b64_e32 v[100:101], 0
	v_mov_b64_e32 v[94:95], 0
	v_mov_b64_e32 v[92:93], 0
	v_mov_b64_e32 v[74:75], 0
	v_mov_b64_e32 v[72:73], 0
	v_mov_b64_e32 v[70:71], 0
	v_mov_b64_e32 v[68:69], 0
	v_mov_b64_e32 v[66:67], 0
	v_mov_b64_e32 v[64:65], 0
	v_mov_b64_e32 v[62:63], 0
	v_mov_b64_e32 v[60:61], 0
	v_mov_b64_e32 v[50:51], 0
	v_mov_b64_e32 v[48:49], 0
	v_mov_b64_e32 v[46:47], 0
	v_mov_b64_e32 v[44:45], 0
	v_mov_b64_e32 v[34:35], 0
	v_mov_b64_e32 v[32:33], 0
	v_mov_b64_e32 v[30:31], 0
	v_mov_b64_e32 v[28:29], 0
	v_mov_b64_e32 v[18:19], 0
	v_mov_b64_e32 v[16:17], 0
	v_mov_b64_e32 v[14:15], 0
	v_mov_b64_e32 v[12:13], 0
	v_mov_b64_e32 v[58:59], 0
	v_mov_b64_e32 v[56:57], 0
	v_mov_b64_e32 v[54:55], 0
	v_mov_b64_e32 v[52:53], 0
	v_mov_b64_e32 v[42:43], 0
	v_mov_b64_e32 v[40:41], 0
	v_mov_b64_e32 v[38:39], 0
	v_mov_b64_e32 v[36:37], 0
	v_mov_b64_e32 v[26:27], 0
	v_mov_b64_e32 v[24:25], 0
	v_mov_b64_e32 v[22:23], 0
	v_mov_b64_e32 v[20:21], 0
	v_mov_b64_e32 v[10:11], 0
	v_mov_b64_e32 v[8:9], 0
	v_mov_b64_e32 v[6:7], 0
	v_mov_b64_e32 v[4:5], 0
	s_cbranch_vccnz .LBB0_1021
	v_mov_b32_e32 v4, 0
	s_mov_b32 s72, 2
	v_mov_b32_e32 v5, 0
	v_mov_b64_e32 v[6:7], 0
	v_mov_b64_e32 v[8:9], 0
	v_mov_b64_e32 v[10:11], 0
	v_mov_b64_e32 v[20:21], 0
	v_mov_b64_e32 v[22:23], 0
	v_mov_b64_e32 v[24:25], 0
	v_mov_b64_e32 v[26:27], 0
	v_mov_b64_e32 v[36:37], 0
	v_mov_b64_e32 v[38:39], 0
	v_mov_b64_e32 v[40:41], 0
	v_mov_b64_e32 v[42:43], 0
	v_mov_b64_e32 v[52:53], 0
	v_mov_b64_e32 v[54:55], 0
	v_mov_b64_e32 v[56:57], 0
	v_mov_b64_e32 v[58:59], 0
	v_mov_b64_e32 v[12:13], 0
	v_mov_b64_e32 v[14:15], 0
	v_mov_b64_e32 v[16:17], 0
	v_mov_b64_e32 v[18:19], 0
	v_mov_b64_e32 v[28:29], 0
	v_mov_b64_e32 v[30:31], 0
	v_mov_b64_e32 v[32:33], 0
	v_mov_b64_e32 v[34:35], 0
	v_mov_b64_e32 v[44:45], 0
	v_mov_b64_e32 v[46:47], 0
	v_mov_b64_e32 v[48:49], 0
	v_mov_b64_e32 v[50:51], 0
	v_mov_b64_e32 v[60:61], 0
	v_mov_b64_e32 v[62:63], 0
	v_mov_b64_e32 v[64:65], 0
	v_mov_b64_e32 v[66:67], 0
	v_mov_b64_e32 v[68:69], 0
	v_mov_b64_e32 v[70:71], 0
	v_mov_b64_e32 v[72:73], 0
	v_mov_b64_e32 v[74:75], 0
	v_mov_b64_e32 v[92:93], 0
	v_mov_b64_e32 v[94:95], 0
	v_mov_b64_e32 v[100:101], 0
	v_mov_b64_e32 v[102:103], 0
	v_mov_b64_e32 v[116:117], 0
	v_mov_b64_e32 v[118:119], 0
	v_mov_b64_e32 v[120:121], 0
	v_mov_b64_e32 v[122:123], 0
	v_mov_b64_e32 v[132:133], 0
	v_mov_b64_e32 v[134:135], 0
	v_mov_b64_e32 v[136:137], 0
	v_mov_b64_e32 v[138:139], 0
	v_mov_b64_e32 v[76:77], 0
	v_mov_b64_e32 v[78:79], 0
	v_mov_b64_e32 v[80:81], 0
	v_mov_b64_e32 v[82:83], 0
	v_mov_b64_e32 v[108:109], 0
	v_mov_b64_e32 v[110:111], 0
	v_mov_b64_e32 v[112:113], 0
	v_mov_b64_e32 v[114:115], 0
	v_mov_b64_e32 v[124:125], 0
	v_mov_b64_e32 v[126:127], 0
	v_mov_b64_e32 v[128:129], 0
	v_mov_b64_e32 v[130:131], 0
	v_mov_b64_e32 v[140:141], 0
	v_mov_b64_e32 v[142:143], 0
	v_mov_b64_e32 v[144:145], 0
	v_mov_b64_e32 v[146:147], 0

; template <class Epi, class Sched, bool ALIGN_EPI = false, bool SP2 = false, bool DRAIN = true, bool XR = false>
; __device__ __forceinline__ void gemm_phase(PG8_LAS unsigned char* lds, const Gemm g, const Sched& S, const Epi& E) {
;     ...
;         const char* nA = has_next ? (const char*)g.A + (size_t)nxt.pm * tstep : cA; const char* nB = has_next ? (const char*)g.Bt + (size_t)nxt.pn * tstep : cB;
;         const char* nX = (XR && has_next) ? (const char*)g.Ax + (size_t)(nxt.pm >> 1) * xstep : cX;
;     ...
;         for (int a = 0; a < 2; ++a)
; #pragma unroll
;             for (int b = 0; b < 2; ++b)
; #pragma unroll
;                 for (int m = 0; m < 4; ++m)
; #pragma unroll
;                     for (int n = 0; n < 2; ++n) acc[a][b][m][n] = (f32x4){0.f, 0.f, 0.f, 0.f};
;         cur = nxt; cA = nA; cB = nB; ++ui;
;         if constexpr (XR) { cX = nX; hasx = (((cur.pm & 1) == 0) == (cur.pn < xnh)); accx[0] = (f32x4){0.f, 0.f, 0.f, 0.f}; accx[1] = (f32x4){0.f, 0.f, 0.f, 0.f}; }
.LBB0_1357:
	s_ashr_i32 s6, s80, 1
	s_ashr_i32 s7, s6, 31
	s_lshl_b64 s[6:7], s[6:7], 13
	v_readlane_b32 s8, v253, 31
	s_add_u32 s52, s8, s6
	v_readlane_b32 s6, v253, 35
	s_addc_u32 s53, s6, s7
	s_andn2_b64 vcc, exec, s[40:41]
	s_cbranch_vccnz .LBB0_1377
	v_mov_b32_e32 v4, v3
	v_mov_b32_e32 v5, v3
	s_and_b64 s[4:5], s[4:5], exec
	v_mov_b32_e32 v2, v3
	v_mov_b32_e32 v14, 0
	v_mov_b64_e32 v[8:9], v[4:5]
	v_mov_b64_e32 v[12:13], v[4:5]
	s_cselect_b32 s88, s53, s59
	s_cselect_b32 s89, s52, s58
	s_mov_b32 s90, 2
	v_mov_b64_e32 v[6:7], v[2:3]
	v_mov_b64_e32 v[10:11], v[2:3]
	v_mov_b32_e32 v15, 0
	v_mov_b64_e32 v[16:17], 0
	v_mov_b64_e32 v[18:19], 0
	v_mov_b64_e32 v[20:21], 0
	v_mov_b64_e32 v[30:31], 0
	v_mov_b64_e32 v[32:33], 0
	v_mov_b64_e32 v[34:35], 0
	v_mov_b64_e32 v[36:37], 0
	v_mov_b64_e32 v[46:47], 0
	v_mov_b64_e32 v[48:49], 0
	v_mov_b64_e32 v[50:51], 0
	v_mov_b64_e32 v[52:53], 0
	v_mov_b64_e32 v[62:63], 0
	v_mov_b64_e32 v[64:65], 0
	v_mov_b64_e32 v[66:67], 0
	v_mov_b64_e32 v[68:69], 0
	v_mov_b64_e32 v[22:23], 0
	v_mov_b64_e32 v[24:25], 0
	v_mov_b64_e32 v[26:27], 0
	v_mov_b64_e32 v[28:29], 0
	v_mov_b64_e32 v[38:39], 0
	v_mov_b64_e32 v[40:41], 0
	v_mov_b64_e32 v[42:43], 0
	v_mov_b64_e32 v[44:45], 0
	v_mov_b64_e32 v[54:55], 0
	v_mov_b64_e32 v[56:57], 0
	v_mov_b64_e32 v[58:59], 0
	v_mov_b64_e32 v[60:61], 0
	v_mov_b64_e32 v[70:71], 0
	v_mov_b64_e32 v[72:73], 0
	v_mov_b64_e32 v[74:75], 0
	v_mov_b64_e32 v[76:77], 0
	v_mov_b64_e32 v[78:79], 0
	v_mov_b64_e32 v[80:81], 0
	v_mov_b64_e32 v[82:83], 0
	v_mov_b64_e32 v[84:85], 0
	v_mov_b64_e32 v[94:95], 0
	v_mov_b64_e32 v[96:97], 0
	v_mov_b64_e32 v[98:99], 0
	v_mov_b64_e32 v[100:101], 0
	v_mov_b64_e32 v[110:111], 0
	v_mov_b64_e32 v[112:113], 0
	v_mov_b64_e32 v[114:115], 0
	v_mov_b64_e32 v[116:117], 0
	v_mov_b64_e32 v[126:127], 0
	v_mov_b64_e32 v[128:129], 0
	v_mov_b64_e32 v[130:131], 0
	v_mov_b64_e32 v[132:133], 0
	v_mov_b64_e32 v[86:87], 0
	v_mov_b64_e32 v[88:89], 0
	v_mov_b64_e32 v[90:91], 0
	v_mov_b64_e32 v[92:93], 0
	v_mov_b64_e32 v[102:103], 0
	v_mov_b64_e32 v[104:105], 0
	v_mov_b64_e32 v[106:107], 0
	v_mov_b64_e32 v[108:109], 0
	v_mov_b64_e32 v[118:119], 0
	v_mov_b64_e32 v[120:121], 0
	v_mov_b64_e32 v[122:123], 0
	v_mov_b64_e32 v[124:125], 0
	v_mov_b64_e32 v[134:135], 0
	v_mov_b64_e32 v[136:137], 0
	v_mov_b64_e32 v[138:139], 0
	v_mov_b64_e32 v[140:141], 0

; template <class Epi, class Sched, bool ALIGN_EPI = false, bool SP2 = false, bool DRAIN = true, bool XR = false>
; __device__ __forceinline__ void gemm_phase(PG8_LAS unsigned char* lds, const Gemm g, const Sched& S, const Epi& E) {
;     ...
;         for (int a = 0; a < 2; ++a)
; #pragma unroll
;             for (int b = 0; b < 2; ++b)
; #pragma unroll
;                 for (int m = 0; m < 4; ++m)
; #pragma unroll
;                     for (int n = 0; n < 2; ++n) acc[a][b][m][n] = (f32x4){0.f, 0.f, 0.f, 0.f};
;         cur = nxt; cA = nA; cB = nB; ++ui;
;         if constexpr (XR) { cX = nX; hasx = (((cur.pm & 1) == 0) == (cur.pn < xnh)); accx[0] = (f32x4){0.f, 0.f, 0.f, 0.f}; accx[1] = (f32x4){0.f, 0.f, 0.f, 0.f}; }
.LBB0_1377:
	v_mov_b32_e32 v4, v3
	v_mov_b32_e32 v5, v3
	v_mov_b32_e32 v2, v3
	v_mov_b32_e32 v141, 0
	v_mov_b64_e32 v[12:13], v[4:5]
	v_mov_b64_e32 v[8:9], v[4:5]
	v_mov_b32_e32 v140, 0
	v_mov_b64_e32 v[138:139], 0
	v_mov_b64_e32 v[136:137], 0
	v_mov_b64_e32 v[134:135], 0
	v_mov_b64_e32 v[124:125], 0
	v_mov_b64_e32 v[122:123], 0
	v_mov_b64_e32 v[120:121], 0
	v_mov_b64_e32 v[118:119], 0
	v_mov_b64_e32 v[108:109], 0
	v_mov_b64_e32 v[106:107], 0
	v_mov_b64_e32 v[104:105], 0
	v_mov_b64_e32 v[102:103], 0
	v_mov_b64_e32 v[92:93], 0
	v_mov_b64_e32 v[90:91], 0
	v_mov_b64_e32 v[88:89], 0
	v_mov_b64_e32 v[86:87], 0
	v_mov_b64_e32 v[132:133], 0
	v_mov_b64_e32 v[130:131], 0
	v_mov_b64_e32 v[128:129], 0
	v_mov_b64_e32 v[126:127], 0
	v_mov_b64_e32 v[116:117], 0
	v_mov_b64_e32 v[114:115], 0
	v_mov_b64_e32 v[112:113], 0
	v_mov_b64_e32 v[110:111], 0
	v_mov_b64_e32 v[100:101], 0
	v_mov_b64_e32 v[98:99], 0
	v_mov_b64_e32 v[96:97], 0
	v_mov_b64_e32 v[94:95], 0
	v_mov_b64_e32 v[84:85], 0
	v_mov_b64_e32 v[82:83], 0
	v_mov_b64_e32 v[80:81], 0
	v_mov_b64_e32 v[78:79], 0
	v_mov_b64_e32 v[76:77], 0
	v_mov_b64_e32 v[74:75], 0
	v_mov_b64_e32 v[72:73], 0
	v_mov_b64_e32 v[70:71], 0
	v_mov_b64_e32 v[60:61], 0
	v_mov_b64_e32 v[58:59], 0
	v_mov_b64_e32 v[56:57], 0
	v_mov_b64_e32 v[54:55], 0
	v_mov_b64_e32 v[44:45], 0
	v_mov_b64_e32 v[42:43], 0
	v_mov_b64_e32 v[40:41], 0
	v_mov_b64_e32 v[38:39], 0
	v_mov_b64_e32 v[28:29], 0
	v_mov_b64_e32 v[26:27], 0
	v_mov_b64_e32 v[24:25], 0
	v_mov_b64_e32 v[22:23], 0
	v_mov_b64_e32 v[68:69], 0
	v_mov_b64_e32 v[66:67], 0
	v_mov_b64_e32 v[64:65], 0
	v_mov_b64_e32 v[62:63], 0
	v_mov_b64_e32 v[52:53], 0
	v_mov_b64_e32 v[50:51], 0
	v_mov_b64_e32 v[48:49], 0
	v_mov_b64_e32 v[46:47], 0
	v_mov_b64_e32 v[36:37], 0
	v_mov_b64_e32 v[34:35], 0
	v_mov_b64_e32 v[32:33], 0
	v_mov_b64_e32 v[30:31], 0
	v_mov_b64_e32 v[20:21], 0
	v_mov_b64_e32 v[18:19], 0
	v_mov_b64_e32 v[16:17], 0
	v_mov_b64_e32 v[14:15], 0
	v_mov_b64_e32 v[10:11], v[2:3]
	v_mov_b64_e32 v[6:7], v[2:3]

; template <class Epi, class Sched, bool ALIGN_EPI = false, bool SP2 = false, bool DRAIN = true, bool XR = false>
; __device__ __forceinline__ void gemm_phase(PG8_LAS unsigned char* lds, const Gemm g, const Sched& S, const Epi& E) {
;     ...
;         const char* nA = has_next ? (const char*)g.A + (size_t)nxt.pm * tstep : cA; const char* nB = has_next ? (const char*)g.Bt + (size_t)nxt.pn * tstep : cB;
;         const char* nX = (XR && has_next) ? (const char*)g.Ax + (size_t)(nxt.pm >> 1) * xstep : cX;
;     ...
;         for (int a = 0; a < 2; ++a)
; #pragma unroll
;             for (int b = 0; b < 2; ++b)
; #pragma unroll
;                 for (int m = 0; m < 4; ++m)
; #pragma unroll
;                     for (int n = 0; n < 2; ++n) acc[a][b][m][n] = (f32x4){0.f, 0.f, 0.f, 0.f};
;         cur = nxt; cA = nA; cB = nB; ++ui;
;         if constexpr (XR) { cX = nX; hasx = (((cur.pm & 1) == 0) == (cur.pn < xnh)); accx[0] = (f32x4){0.f, 0.f, 0.f, 0.f}; accx[1] = (f32x4){0.f, 0.f, 0.f, 0.f}; }
.LBB0_1649:
	s_ashr_i32 s6, s92, 1
	s_ashr_i32 s7, s6, 31
	s_lshl_b64 s[6:7], s[6:7], 17
	s_add_u32 s28, s55, s6
	s_addc_u32 s29, s56, s7
	s_andn2_b64 vcc, exec, s[18:19]
	s_cbranch_vccnz .LBB0_1668
	s_and_b64 s[0:1], s[0:1], exec
	s_cselect_b32 s0, s29, s43
	s_cselect_b32 s1, s28, s42
	s_add_u32 s93, s24, s62
	s_addc_u32 s39, s25, 0
	s_add_u32 s50, s26, s61
	s_addc_u32 s96, s27, 0
	v_mov_b32_e32 v4, v3
	v_mov_b32_e32 v5, v3
	s_add_u32 s97, s1, s61
	v_mov_b32_e32 v2, v3
	v_mov_b32_e32 v14, 0
	v_mov_b64_e32 v[8:9], v[4:5]
	v_mov_b64_e32 v[12:13], v[4:5]
	s_addc_u32 s90, s0, 0
	s_mov_b32 s89, 0
	v_mov_b64_e32 v[6:7], v[2:3]
	v_mov_b64_e32 v[10:11], v[2:3]
	v_mov_b32_e32 v15, 0
	v_mov_b64_e32 v[16:17], 0
	v_mov_b64_e32 v[18:19], 0
	v_mov_b64_e32 v[20:21], 0
	v_mov_b64_e32 v[30:31], 0
	v_mov_b64_e32 v[32:33], 0
	v_mov_b64_e32 v[34:35], 0
	v_mov_b64_e32 v[36:37], 0
	v_mov_b64_e32 v[46:47], 0
	v_mov_b64_e32 v[48:49], 0
	v_mov_b64_e32 v[50:51], 0
	v_mov_b64_e32 v[52:53], 0
	v_mov_b64_e32 v[62:63], 0
	v_mov_b64_e32 v[64:65], 0
	v_mov_b64_e32 v[66:67], 0
	v_mov_b64_e32 v[68:69], 0
	v_mov_b64_e32 v[22:23], 0
	v_mov_b64_e32 v[24:25], 0
	v_mov_b64_e32 v[26:27], 0
	v_mov_b64_e32 v[28:29], 0
	v_mov_b64_e32 v[38:39], 0
	v_mov_b64_e32 v[40:41], 0
	v_mov_b64_e32 v[42:43], 0
	v_mov_b64_e32 v[44:45], 0
	v_mov_b64_e32 v[54:55], 0
	v_mov_b64_e32 v[56:57], 0
	v_mov_b64_e32 v[58:59], 0
	v_mov_b64_e32 v[60:61], 0
	v_mov_b64_e32 v[70:71], 0
	v_mov_b64_e32 v[72:73], 0
	v_mov_b64_e32 v[74:75], 0
	v_mov_b64_e32 v[76:77], 0
	v_mov_b64_e32 v[78:79], 0
	v_mov_b64_e32 v[80:81], 0
	v_mov_b64_e32 v[82:83], 0
	v_mov_b64_e32 v[84:85], 0
	v_mov_b64_e32 v[94:95], 0
	v_mov_b64_e32 v[96:97], 0
	v_mov_b64_e32 v[98:99], 0
	v_mov_b64_e32 v[100:101], 0
	v_mov_b64_e32 v[110:111], 0
	v_mov_b64_e32 v[112:113], 0
	v_mov_b64_e32 v[114:115], 0
	v_mov_b64_e32 v[116:117], 0
	v_mov_b64_e32 v[126:127], 0
	v_mov_b64_e32 v[128:129], 0
	v_mov_b64_e32 v[130:131], 0
	v_mov_b64_e32 v[132:133], 0
	v_mov_b64_e32 v[86:87], 0
	v_mov_b64_e32 v[88:89], 0
	v_mov_b64_e32 v[90:91], 0
	v_mov_b64_e32 v[92:93], 0
	v_mov_b64_e32 v[102:103], 0
	v_mov_b64_e32 v[104:105], 0
	v_mov_b64_e32 v[106:107], 0
	v_mov_b64_e32 v[108:109], 0
	v_mov_b64_e32 v[118:119], 0
	v_mov_b64_e32 v[120:121], 0
	v_mov_b64_e32 v[122:123], 0
	v_mov_b64_e32 v[124:125], 0
	v_mov_b64_e32 v[134:135], 0
	v_mov_b64_e32 v[136:137], 0
	v_mov_b64_e32 v[138:139], 0
	v_mov_b64_e32 v[140:141], 0
	s_branch .LBB0_1652
